# QK-norm in-proj epilogue: the 32 cross-lane sum-of-squares reductions use v_permlane16_swap/v_permlane32_swap (VALU) instead of ds_bpermute LDS round trips
# baseline (speedup 1.0000x reference)
.LBB0_137:
	s_andn2_b64 vcc, exec, s[48:49]
	s_cbranch_vccnz .LBB0_171
	v_pk_mul_f32 v[178:179], v[128:129], v[166:167] op_sel_hi:[1,0]
	v_pk_mul_f32 v[180:181], v[126:127], v[166:167] op_sel_hi:[1,0]
	v_mul_f32_e32 v149, v179, v179
	v_mul_f32_e32 v147, v181, v181
	v_pk_mul_f32 v[208:209], v[122:123], v[166:167] op_sel_hi:[1,0]
	v_fmac_f32_e32 v147, v180, v180
	v_fmac_f32_e32 v149, v178, v178
	v_and_b32_e32 v145, 64, v198
	v_add_f32_e32 v147, v147, v149
	v_mul_f32_e32 v149, v209, v209
	v_xor_b32_e32 v143, 16, v198
	v_add_u32_e32 v145, 64, v145
	v_pk_mul_f32 v[202:203], v[124:125], v[166:167] op_sel_hi:[1,0]
	v_fmac_f32_e32 v149, v208, v208
	v_cmp_lt_i32_e32 vcc, v143, v145
	v_add_f32_e32 v147, v149, v147
	v_mul_f32_e32 v149, v203, v203
	v_cndmask_b32_e32 v143, v198, v143, vcc
	v_fmac_f32_e32 v149, v202, v202
	v_lshlrev_b32_e32 v143, 2, v143
	v_add_f32_e32 v147, v149, v147
	v_mov_b32_e32 v149, v147
	s_nop 1
	v_permlane16_swap_b32_e32 v147, v149
	v_xor_b32_e32 v151, 32, v198
	v_cmp_lt_i32_e32 vcc, v151, v145
	s_waitcnt lgkmcnt(0)
	v_add_f32_e32 v147, v147, v149
	v_cndmask_b32_e32 v145, v198, v151, vcc
	v_lshlrev_b32_e32 v145, 2, v145
	v_mov_b32_e32 v149, v147
	s_nop 1
	v_permlane32_swap_b32_e32 v147, v149
	s_and_saveexec_b64 s[48:49], s[6:7]
	s_cbranch_execz .LBB0_140
	s_waitcnt lgkmcnt(0)
	v_add_f32_e32 v147, v147, v149
	ds_write_b32 v183, v147
.LBB0_140:
	s_or_b64 exec, exec, s[48:49]
	v_mov_b32_e32 v167, v166
	v_mov_b32_e32 v178, v166
	v_mov_b32_e32 v179, v166
	v_pk_mul_f32 v[180:181], v[120:121], v[178:179]
	v_pk_mul_f32 v[202:203], v[118:119], v[166:167]
	s_waitcnt lgkmcnt(0)
	v_mul_f32_e32 v149, v181, v181
	v_mul_f32_e32 v147, v203, v203
	v_pk_mul_f32 v[208:209], v[114:115], v[166:167]
	v_fmac_f32_e32 v147, v202, v202
	v_fmac_f32_e32 v149, v180, v180
	v_add_f32_e32 v147, v147, v149
	v_mul_f32_e32 v149, v209, v209
	v_pk_mul_f32 v[178:179], v[116:117], v[178:179]
	v_fmac_f32_e32 v149, v208, v208
	v_add_f32_e32 v147, v149, v147
	v_mul_f32_e32 v149, v179, v179
	v_fmac_f32_e32 v149, v178, v178
	v_add_f32_e32 v147, v149, v147
	v_mov_b32_e32 v149, v147
	s_nop 1
	v_permlane16_swap_b32_e32 v147, v149
	s_waitcnt lgkmcnt(0)
	v_add_f32_e32 v147, v147, v149
	v_mov_b32_e32 v149, v147
	s_nop 1
	v_permlane32_swap_b32_e32 v147, v149
	s_and_saveexec_b64 s[48:49], s[6:7]
	s_cbranch_execz .LBB0_142
	s_waitcnt lgkmcnt(0)
	v_add_f32_e32 v147, v147, v149
	ds_write_b32 v183, v147 offset:16
.LBB0_142:
	s_or_b64 exec, exec, s[48:49]
	v_pk_mul_f32 v[178:179], v[112:113], v[164:165] op_sel_hi:[1,0]
	v_pk_mul_f32 v[180:181], v[110:111], v[164:165] op_sel_hi:[1,0]
	s_waitcnt lgkmcnt(0)
	v_mul_f32_e32 v149, v179, v179
	v_mul_f32_e32 v147, v181, v181
	v_pk_mul_f32 v[208:209], v[106:107], v[164:165] op_sel_hi:[1,0]
	v_fmac_f32_e32 v147, v180, v180
	v_fmac_f32_e32 v149, v178, v178
	v_add_f32_e32 v147, v147, v149
	v_mul_f32_e32 v149, v209, v209
	v_pk_mul_f32 v[202:203], v[108:109], v[164:165] op_sel_hi:[1,0]
	v_fmac_f32_e32 v149, v208, v208
	v_add_f32_e32 v147, v149, v147
	v_mul_f32_e32 v149, v203, v203
	v_fmac_f32_e32 v149, v202, v202
	v_add_f32_e32 v147, v149, v147
	v_mov_b32_e32 v149, v147
	s_nop 1
	v_permlane16_swap_b32_e32 v147, v149
	s_waitcnt lgkmcnt(0)
	v_add_f32_e32 v147, v147, v149
	v_mov_b32_e32 v149, v147
	s_nop 1
	v_permlane32_swap_b32_e32 v147, v149
	s_and_saveexec_b64 s[48:49], s[6:7]
	s_cbranch_execz .LBB0_144
	s_waitcnt lgkmcnt(0)
	v_add_f32_e32 v147, v147, v149
	ds_write_b32 v183, v147 offset:512
.LBB0_144:
	s_or_b64 exec, exec, s[48:49]
	v_mov_b32_e32 v165, v164
	v_mov_b32_e32 v178, v164
	v_mov_b32_e32 v179, v164
	v_pk_mul_f32 v[180:181], v[104:105], v[178:179]
	v_pk_mul_f32 v[202:203], v[102:103], v[164:165]
	s_waitcnt lgkmcnt(0)
	v_mul_f32_e32 v149, v181, v181
	v_mul_f32_e32 v147, v203, v203
	v_pk_mul_f32 v[208:209], v[98:99], v[164:165]
	v_fmac_f32_e32 v147, v202, v202
	v_fmac_f32_e32 v149, v180, v180
	v_add_f32_e32 v147, v147, v149
	v_mul_f32_e32 v149, v209, v209
	v_pk_mul_f32 v[178:179], v[100:101], v[178:179]
	v_fmac_f32_e32 v149, v208, v208
	v_add_f32_e32 v147, v149, v147
	v_mul_f32_e32 v149, v179, v179
	v_fmac_f32_e32 v149, v178, v178
	v_add_f32_e32 v147, v149, v147
	v_mov_b32_e32 v149, v147
	s_nop 1
	v_permlane16_swap_b32_e32 v147, v149
	s_waitcnt lgkmcnt(0)
	v_add_f32_e32 v147, v147, v149
	v_mov_b32_e32 v149, v147
	s_nop 1
	v_permlane32_swap_b32_e32 v147, v149
	s_and_saveexec_b64 s[48:49], s[6:7]
	s_cbranch_execz .LBB0_146
	s_waitcnt lgkmcnt(0)
	v_add_f32_e32 v147, v147, v149
	ds_write_b32 v183, v147 offset:528
.LBB0_146:
	s_or_b64 exec, exec, s[48:49]
	v_pk_mul_f32 v[178:179], v[96:97], v[162:163] op_sel_hi:[1,0]
	v_pk_mul_f32 v[180:181], v[94:95], v[162:163] op_sel_hi:[1,0]
	s_waitcnt lgkmcnt(0)
	v_mul_f32_e32 v149, v179, v179
	v_mul_f32_e32 v147, v181, v181
	v_pk_mul_f32 v[208:209], v[90:91], v[162:163] op_sel_hi:[1,0]
	v_fmac_f32_e32 v147, v180, v180
	v_fmac_f32_e32 v149, v178, v178
	v_add_f32_e32 v147, v147, v149
	v_mul_f32_e32 v149, v209, v209
	v_pk_mul_f32 v[202:203], v[92:93], v[162:163] op_sel_hi:[1,0]
	v_fmac_f32_e32 v149, v208, v208
	v_add_f32_e32 v147, v149, v147
	v_mul_f32_e32 v149, v203, v203
	v_fmac_f32_e32 v149, v202, v202
	v_add_f32_e32 v147, v149, v147
	v_mov_b32_e32 v149, v147
	s_nop 1
	v_permlane16_swap_b32_e32 v147, v149
	s_waitcnt lgkmcnt(0)
	v_add_f32_e32 v147, v147, v149
	v_mov_b32_e32 v149, v147
	s_nop 1
	v_permlane32_swap_b32_e32 v147, v149
	s_and_saveexec_b64 s[48:49], s[6:7]
	s_cbranch_execz .LBB0_148
	s_waitcnt lgkmcnt(0)
	v_add_f32_e32 v147, v147, v149
	ds_write_b32 v183, v147 offset:1024
.LBB0_148:
	s_or_b64 exec, exec, s[48:49]
	v_mov_b32_e32 v163, v162
	v_mov_b32_e32 v178, v162
	v_mov_b32_e32 v179, v162
	v_pk_mul_f32 v[180:181], v[88:89], v[178:179]
	v_pk_mul_f32 v[202:203], v[86:87], v[162:163]
	s_waitcnt lgkmcnt(0)
	v_mul_f32_e32 v149, v181, v181
	v_mul_f32_e32 v147, v203, v203
	v_pk_mul_f32 v[208:209], v[82:83], v[162:163]
	v_fmac_f32_e32 v147, v202, v202
	v_fmac_f32_e32 v149, v180, v180
	v_add_f32_e32 v147, v147, v149
	v_mul_f32_e32 v149, v209, v209
	v_pk_mul_f32 v[178:179], v[84:85], v[178:179]
	v_fmac_f32_e32 v149, v208, v208
	v_add_f32_e32 v147, v149, v147
	v_mul_f32_e32 v149, v179, v179
	v_fmac_f32_e32 v149, v178, v178
	v_add_f32_e32 v147, v149, v147
	v_mov_b32_e32 v149, v147
	s_nop 1
	v_permlane16_swap_b32_e32 v147, v149
	s_waitcnt lgkmcnt(0)
	v_add_f32_e32 v147, v147, v149
	v_mov_b32_e32 v149, v147
	s_nop 1
	v_permlane32_swap_b32_e32 v147, v149
	s_and_saveexec_b64 s[48:49], s[6:7]
	s_cbranch_execz .LBB0_150
	s_waitcnt lgkmcnt(0)
	v_add_f32_e32 v147, v147, v149
	ds_write_b32 v183, v147 offset:1040
.LBB0_150:
	s_or_b64 exec, exec, s[48:49]
	v_pk_mul_f32 v[178:179], v[80:81], v[160:161] op_sel_hi:[1,0]
	v_pk_mul_f32 v[180:181], v[78:79], v[160:161] op_sel_hi:[1,0]
	s_waitcnt lgkmcnt(0)
	v_mul_f32_e32 v149, v179, v179
	v_mul_f32_e32 v147, v181, v181
	v_pk_mul_f32 v[208:209], v[74:75], v[160:161] op_sel_hi:[1,0]
	v_fmac_f32_e32 v147, v180, v180
	v_fmac_f32_e32 v149, v178, v178
	v_add_f32_e32 v147, v147, v149
	v_mul_f32_e32 v149, v209, v209
	v_pk_mul_f32 v[202:203], v[76:77], v[160:161] op_sel_hi:[1,0]
	v_fmac_f32_e32 v149, v208, v208
	v_add_f32_e32 v147, v149, v147
	v_mul_f32_e32 v149, v203, v203
	v_fmac_f32_e32 v149, v202, v202
	v_add_f32_e32 v147, v149, v147
	v_mov_b32_e32 v149, v147
	s_nop 1
	v_permlane16_swap_b32_e32 v147, v149
	s_waitcnt lgkmcnt(0)
	v_add_f32_e32 v147, v147, v149
	v_mov_b32_e32 v149, v147
	s_nop 1
	v_permlane32_swap_b32_e32 v147, v149
	s_and_saveexec_b64 s[48:49], s[6:7]
	s_cbranch_execz .LBB0_152
	s_waitcnt lgkmcnt(0)
	v_add_f32_e32 v147, v147, v149
	ds_write_b32 v183, v147 offset:1536
.LBB0_152:
	s_or_b64 exec, exec, s[48:49]
	v_mov_b32_e32 v161, v160
	v_mov_b32_e32 v178, v160
	v_mov_b32_e32 v179, v160
	v_pk_mul_f32 v[180:181], v[72:73], v[178:179]
	v_pk_mul_f32 v[202:203], v[70:71], v[160:161]
	s_waitcnt lgkmcnt(0)
	v_mul_f32_e32 v149, v181, v181
	v_mul_f32_e32 v147, v203, v203
	v_pk_mul_f32 v[208:209], v[66:67], v[160:161]
	v_fmac_f32_e32 v147, v202, v202
	v_fmac_f32_e32 v149, v180, v180
	v_add_f32_e32 v147, v147, v149
	v_mul_f32_e32 v149, v209, v209
	v_pk_mul_f32 v[178:179], v[68:69], v[178:179]
	v_fmac_f32_e32 v149, v208, v208
	v_add_f32_e32 v147, v149, v147
	v_mul_f32_e32 v149, v179, v179
	v_fmac_f32_e32 v149, v178, v178
	v_add_f32_e32 v147, v149, v147
	v_mov_b32_e32 v149, v147
	s_nop 1
	v_permlane16_swap_b32_e32 v147, v149
	s_waitcnt lgkmcnt(0)
	v_add_f32_e32 v147, v147, v149
	v_mov_b32_e32 v149, v147
	s_nop 1
	v_permlane32_swap_b32_e32 v147, v149
	s_and_saveexec_b64 s[48:49], s[6:7]
	s_cbranch_execz .LBB0_154
	s_waitcnt lgkmcnt(0)
	v_add_f32_e32 v147, v147, v149
	ds_write_b32 v183, v147 offset:1552
.LBB0_154:
	s_or_b64 exec, exec, s[48:49]
	v_pk_mul_f32 v[178:179], v[64:65], v[158:159] op_sel_hi:[1,0]
	v_pk_mul_f32 v[180:181], v[62:63], v[158:159] op_sel_hi:[1,0]
	s_waitcnt lgkmcnt(0)
	v_mul_f32_e32 v149, v179, v179
	v_mul_f32_e32 v147, v181, v181
	v_pk_mul_f32 v[208:209], v[58:59], v[158:159] op_sel_hi:[1,0]
	v_fmac_f32_e32 v147, v180, v180
	v_fmac_f32_e32 v149, v178, v178
	v_add_f32_e32 v147, v147, v149
	v_mul_f32_e32 v149, v209, v209
	v_pk_mul_f32 v[202:203], v[60:61], v[158:159] op_sel_hi:[1,0]
	v_fmac_f32_e32 v149, v208, v208
	v_add_f32_e32 v147, v149, v147
	v_mul_f32_e32 v149, v203, v203
	v_fmac_f32_e32 v149, v202, v202
	v_add_f32_e32 v147, v149, v147
	v_mov_b32_e32 v149, v147
	s_nop 1
	v_permlane16_swap_b32_e32 v147, v149
	s_waitcnt lgkmcnt(0)
	v_add_f32_e32 v147, v147, v149
	v_mov_b32_e32 v149, v147
	s_nop 1
	v_permlane32_swap_b32_e32 v147, v149
	s_and_saveexec_b64 s[48:49], s[6:7]
	s_cbranch_execz .LBB0_156
	s_waitcnt lgkmcnt(0)
	v_add_f32_e32 v147, v147, v149
	ds_write_b32 v184, v147
.LBB0_156:
	s_or_b64 exec, exec, s[48:49]
	v_mov_b32_e32 v159, v158
	v_mov_b32_e32 v178, v158
	v_mov_b32_e32 v179, v158
	v_pk_mul_f32 v[180:181], v[56:57], v[178:179]
	v_pk_mul_f32 v[202:203], v[54:55], v[158:159]
	s_waitcnt lgkmcnt(0)
	v_mul_f32_e32 v149, v181, v181
	v_mul_f32_e32 v147, v203, v203
	v_pk_mul_f32 v[208:209], v[50:51], v[158:159]
	v_fmac_f32_e32 v147, v202, v202
	v_fmac_f32_e32 v149, v180, v180
	v_add_f32_e32 v147, v147, v149
	v_mul_f32_e32 v149, v209, v209
	v_pk_mul_f32 v[178:179], v[52:53], v[178:179]
	v_fmac_f32_e32 v149, v208, v208
	v_add_f32_e32 v147, v149, v147
	v_mul_f32_e32 v149, v179, v179
	v_fmac_f32_e32 v149, v178, v178
	v_add_f32_e32 v147, v149, v147
	v_mov_b32_e32 v149, v147
	s_nop 1
	v_permlane16_swap_b32_e32 v147, v149
	s_waitcnt lgkmcnt(0)
	v_add_f32_e32 v147, v147, v149
	v_mov_b32_e32 v149, v147
	s_nop 1
	v_permlane32_swap_b32_e32 v147, v149
	s_and_saveexec_b64 s[48:49], s[6:7]
	s_cbranch_execz .LBB0_158
	s_waitcnt lgkmcnt(0)
	v_add_f32_e32 v147, v147, v149
	ds_write_b32 v184, v147 offset:16
.LBB0_158:
	s_or_b64 exec, exec, s[48:49]
	v_pk_mul_f32 v[178:179], v[48:49], v[172:173] op_sel_hi:[1,0]
	v_pk_mul_f32 v[180:181], v[46:47], v[172:173] op_sel_hi:[1,0]
	s_waitcnt lgkmcnt(0)
	v_mul_f32_e32 v149, v179, v179
	v_mul_f32_e32 v147, v181, v181
	v_pk_mul_f32 v[208:209], v[42:43], v[172:173] op_sel_hi:[1,0]
	v_fmac_f32_e32 v147, v180, v180
	v_fmac_f32_e32 v149, v178, v178
	v_add_f32_e32 v147, v147, v149
	v_mul_f32_e32 v149, v209, v209
	v_pk_mul_f32 v[202:203], v[44:45], v[172:173] op_sel_hi:[1,0]
	v_fmac_f32_e32 v149, v208, v208
	v_add_f32_e32 v147, v149, v147
	v_mul_f32_e32 v149, v203, v203
	v_fmac_f32_e32 v149, v202, v202
	v_add_f32_e32 v147, v149, v147
	v_mov_b32_e32 v149, v147
	s_nop 1
	v_permlane16_swap_b32_e32 v147, v149
	s_waitcnt lgkmcnt(0)
	v_add_f32_e32 v147, v147, v149
	v_mov_b32_e32 v149, v147
	s_nop 1
	v_permlane32_swap_b32_e32 v147, v149
	s_and_saveexec_b64 s[48:49], s[6:7]
	s_cbranch_execz .LBB0_160
	s_waitcnt lgkmcnt(0)
	v_add_f32_e32 v147, v147, v149
	ds_write_b32 v185, v147
.LBB0_160:
	s_or_b64 exec, exec, s[48:49]
	v_mov_b32_e32 v173, v172
	v_mov_b32_e32 v178, v172
	v_mov_b32_e32 v179, v172
	v_pk_mul_f32 v[180:181], v[40:41], v[178:179]
	v_pk_mul_f32 v[202:203], v[38:39], v[172:173]
	s_waitcnt lgkmcnt(0)
	v_mul_f32_e32 v149, v181, v181
	v_mul_f32_e32 v147, v203, v203
	v_pk_mul_f32 v[208:209], v[34:35], v[172:173]
	v_fmac_f32_e32 v147, v202, v202
	v_fmac_f32_e32 v149, v180, v180
	v_add_f32_e32 v147, v147, v149
	v_mul_f32_e32 v149, v209, v209
	v_pk_mul_f32 v[178:179], v[36:37], v[178:179]
	v_fmac_f32_e32 v149, v208, v208
	v_add_f32_e32 v147, v149, v147
	v_mul_f32_e32 v149, v179, v179
	v_fmac_f32_e32 v149, v178, v178
	v_add_f32_e32 v147, v149, v147
	v_mov_b32_e32 v149, v147
	s_nop 1
	v_permlane16_swap_b32_e32 v147, v149
	s_waitcnt lgkmcnt(0)
	v_add_f32_e32 v147, v147, v149
	v_mov_b32_e32 v149, v147
	s_nop 1
	v_permlane32_swap_b32_e32 v147, v149
	s_and_saveexec_b64 s[48:49], s[6:7]
	s_cbranch_execz .LBB0_162
	s_waitcnt lgkmcnt(0)
	v_add_f32_e32 v147, v147, v149
	ds_write_b32 v185, v147 offset:16
.LBB0_162:
	s_or_b64 exec, exec, s[48:49]
	v_pk_mul_f32 v[178:179], v[32:33], v[170:171] op_sel_hi:[1,0]
	v_pk_mul_f32 v[180:181], v[30:31], v[170:171] op_sel_hi:[1,0]
	s_waitcnt lgkmcnt(0)
	v_mul_f32_e32 v149, v179, v179
	v_mul_f32_e32 v147, v181, v181
	v_pk_mul_f32 v[208:209], v[26:27], v[170:171] op_sel_hi:[1,0]
	v_fmac_f32_e32 v147, v180, v180
	v_fmac_f32_e32 v149, v178, v178
	v_add_f32_e32 v147, v147, v149
	v_mul_f32_e32 v149, v209, v209
	v_pk_mul_f32 v[202:203], v[28:29], v[170:171] op_sel_hi:[1,0]
	v_fmac_f32_e32 v149, v208, v208
	v_add_f32_e32 v147, v149, v147
	v_mul_f32_e32 v149, v203, v203
	v_fmac_f32_e32 v149, v202, v202
	v_add_f32_e32 v147, v149, v147
	v_mov_b32_e32 v149, v147
	s_nop 1
	v_permlane16_swap_b32_e32 v147, v149
	s_waitcnt lgkmcnt(0)
	v_add_f32_e32 v147, v147, v149
	v_mov_b32_e32 v149, v147
	s_nop 1
	v_permlane32_swap_b32_e32 v147, v149
	s_and_saveexec_b64 s[48:49], s[6:7]
	s_cbranch_execz .LBB0_164
	s_waitcnt lgkmcnt(0)
	v_add_f32_e32 v147, v147, v149
	ds_write_b32 v186, v147
.LBB0_164:
	s_or_b64 exec, exec, s[48:49]
	v_mov_b32_e32 v171, v170
	v_mov_b32_e32 v178, v170
	v_mov_b32_e32 v179, v170
	v_pk_mul_f32 v[180:181], v[24:25], v[178:179]
	v_pk_mul_f32 v[202:203], v[22:23], v[170:171]
	s_waitcnt lgkmcnt(0)
	v_mul_f32_e32 v149, v181, v181
	v_mul_f32_e32 v147, v203, v203
	v_pk_mul_f32 v[208:209], v[18:19], v[170:171]
	v_fmac_f32_e32 v147, v202, v202
	v_fmac_f32_e32 v149, v180, v180
	v_add_f32_e32 v147, v147, v149
	v_mul_f32_e32 v149, v209, v209
	v_pk_mul_f32 v[178:179], v[20:21], v[178:179]
	v_fmac_f32_e32 v149, v208, v208
	v_add_f32_e32 v147, v149, v147
	v_mul_f32_e32 v149, v179, v179
	v_fmac_f32_e32 v149, v178, v178
	v_add_f32_e32 v147, v149, v147
	v_mov_b32_e32 v149, v147
	s_nop 1
	v_permlane16_swap_b32_e32 v147, v149
	s_waitcnt lgkmcnt(0)
	v_add_f32_e32 v147, v147, v149
	v_mov_b32_e32 v149, v147
	s_nop 1
	v_permlane32_swap_b32_e32 v147, v149
	s_and_saveexec_b64 s[48:49], s[6:7]
	s_cbranch_execz .LBB0_166
	s_waitcnt lgkmcnt(0)
	v_add_f32_e32 v147, v147, v149
	ds_write_b32 v186, v147 offset:16
.LBB0_166:
	s_or_b64 exec, exec, s[48:49]
	v_pk_mul_f32 v[178:179], v[16:17], v[168:169] op_sel_hi:[1,0]
	v_pk_mul_f32 v[180:181], v[14:15], v[168:169] op_sel_hi:[1,0]
	s_waitcnt lgkmcnt(0)
	v_mul_f32_e32 v149, v179, v179
	v_mul_f32_e32 v147, v181, v181
	v_pk_mul_f32 v[208:209], v[10:11], v[168:169] op_sel_hi:[1,0]
	v_fmac_f32_e32 v147, v180, v180
	v_fmac_f32_e32 v149, v178, v178
	v_add_f32_e32 v147, v147, v149
	v_mul_f32_e32 v149, v209, v209
	v_pk_mul_f32 v[202:203], v[12:13], v[168:169] op_sel_hi:[1,0]
	v_fmac_f32_e32 v149, v208, v208
	v_add_f32_e32 v147, v149, v147
	v_mul_f32_e32 v149, v203, v203
	v_fmac_f32_e32 v149, v202, v202
	v_add_f32_e32 v147, v149, v147
	v_mov_b32_e32 v149, v147
	s_nop 1
	v_permlane16_swap_b32_e32 v147, v149
	s_waitcnt lgkmcnt(0)
	v_add_f32_e32 v147, v147, v149
	v_mov_b32_e32 v149, v147
	s_nop 1
	v_permlane32_swap_b32_e32 v147, v149
	s_and_saveexec_b64 s[48:49], s[6:7]
	s_cbranch_execz .LBB0_168
	s_waitcnt lgkmcnt(0)
	v_add_f32_e32 v147, v147, v149
	ds_write_b32 v187, v147
.LBB0_168:
	s_or_b64 exec, exec, s[48:49]
	v_mov_b32_e32 v169, v168
	v_mov_b32_e32 v178, v168
	v_mov_b32_e32 v179, v168
	v_pk_mul_f32 v[180:181], v[8:9], v[178:179]
	v_pk_mul_f32 v[202:203], v[6:7], v[168:169]
	s_waitcnt lgkmcnt(0)
	v_mul_f32_e32 v149, v181, v181
	v_mul_f32_e32 v147, v203, v203
	v_pk_mul_f32 v[208:209], v[2:3], v[168:169]
	v_fmac_f32_e32 v147, v202, v202
	v_fmac_f32_e32 v149, v180, v180
	v_add_f32_e32 v147, v147, v149
	v_mul_f32_e32 v149, v209, v209
	v_pk_mul_f32 v[178:179], v[4:5], v[178:179]
	v_fmac_f32_e32 v149, v208, v208
	v_add_f32_e32 v147, v149, v147
	v_mul_f32_e32 v149, v179, v179
	v_fmac_f32_e32 v149, v178, v178
	v_add_f32_e32 v147, v149, v147
	v_mov_b32_e32 v143, v147
	s_nop 1
	v_permlane16_swap_b32_e32 v147, v143
	s_waitcnt lgkmcnt(0)
	v_add_f32_e32 v143, v147, v143
	v_mov_b32_e32 v145, v143
	s_nop 1
	v_permlane32_swap_b32_e32 v143, v145
	s_and_saveexec_b64 s[48:49], s[6:7]
	s_cbranch_execz .LBB0_170
	s_waitcnt lgkmcnt(0)
	v_add_f32_e32 v143, v143, v145
	ds_write_b32 v187, v143 offset:16
